# gate GEMM epilogue: 4-byte touch loads of the next three row batches of gate logits issued while the first batch is in flight
# baseline (speedup 1.0000x reference)
; __device__ __forceinline__ float sigmoidf_(float x) { return __builtin_amdgcn_rcpf(1.f + __expf(-x)); }
; __device__ __forceinline__ unsigned cvt_pk_bf16(float lo, float hi) { unsigned r; asm volatile("v_cvt_pk_bf16_f32 %0, %1, %2" : "=v"(r) : "v"(lo), "v"(hi)); return r; }
;     __device__ __forceinline__ void operator()(const f32x4 (&acc)[2][2][4][2], const Unit& u, int wr, int wc, int fr, int fq) const {
;     ...
;                 for (int m = 0; m < 4; ++m) { const size_t row = (size_t)(row0 + ai * HALF + m * 16);
;                     const u32x4 gl = glv[m], t = tv[m];
;                     const f32x4 v0 = acc[ai][bj][m][0], v1 = acc[ai][bj][m][1];
;                     float r[8];
;                     r[0] = sigmoidf_(bflo(gl.x) + b0[0]) * v0[0]; r[1] = sigmoidf_(bfhi(gl.x) + b0[1]) * v0[1];
;                     r[2] = sigmoidf_(bflo(gl.y) + b0[2]) * v0[2]; r[3] = sigmoidf_(bfhi(gl.y) + b0[3]) * v0[3];
;                     r[4] = sigmoidf_(bflo(gl.z) + b1[0]) * v1[0]; r[5] = sigmoidf_(bfhi(gl.z) + b1[1]) * v1[1];
;                     r[6] = sigmoidf_(bflo(gl.w) + b1[2]) * v1[2]; r[7] = sigmoidf_(bfhi(gl.w) + b1[3]) * v1[3];
;                     if (which == 0) { u32x4 w; w.x = cvt_pk_bf16(r[0], r[1]); w.y = cvt_pk_bf16(r[2], r[3]); w.z = cvt_pk_bf16(r[4], r[5]); w.w = cvt_pk_bf16(r[6], r[7]);
;                         *(u32x4*)(T1 + row * 1024 + col) = w; }
;                     else { u32x4 w; w.x = cvt_pk_bf16(r[0] + bflo(t.x), r[1] + bfhi(t.x)); w.y = cvt_pk_bf16(r[2] + bflo(t.y), r[3] + bfhi(t.y));
;                         w.z = cvt_pk_bf16(r[4] + bflo(t.z), r[5] + bfhi(t.z)); w.w = cvt_pk_bf16(r[6] + bflo(t.w), r[7] + bfhi(t.w));
;                         *(u32x4*)(MG + row * 1024 + col) = w; } } } }
.LBB0_871:
	s_mov_b32 s98, 0xf0000
	s_mov_b32 s99, 0
	global_load_dword v228, v[196:197], off offset:3712
	global_load_dword v229, v[198:199], off offset:3712
	global_load_dword v230, v[200:201], off offset:3712
	global_load_dword v231, v[202:203], off offset:3712
	v_lshl_add_u64 v[240:241], v[196:197], 0, s[98:99]
	global_load_dword v232, v[240:241], off offset:3456
	global_load_dword v233, v[240:241], off offset:3712
	v_lshl_add_u64 v[240:241], v[198:199], 0, s[98:99]
	global_load_dword v234, v[240:241], off offset:3456
	global_load_dword v235, v[240:241], off offset:3712
	v_lshl_add_u64 v[240:241], v[200:201], 0, s[98:99]
	global_load_dword v236, v[240:241], off offset:3456
	global_load_dword v237, v[240:241], off offset:3712
	v_lshl_add_u64 v[240:241], v[202:203], 0, s[98:99]
	global_load_dword v238, v[240:241], off offset:3456
	global_load_dword v239, v[240:241], off offset:3712
	s_waitcnt vmcnt(12)
	v_lshlrev_b32_e32 v195, 16, v164
	v_and_b32_e32 v164, 0xffff0000, v164
	v_add_f32_e32 v164, v109, v164
	v_lshlrev_b32_e32 v205, 16, v165
	v_mul_f32_e32 v164, 0xbfb8aa3b, v164
	v_add_f32_e32 v205, v110, v205
	v_exp_f32_e32 v164, v164
	v_mul_f32_e32 v205, 0xbfb8aa3b, v205
	v_exp_f32_e32 v205, v205
	v_add_f32_e32 v195, v108, v195
	v_mul_f32_e32 v195, 0xbfb8aa3b, v195
	v_exp_f32_e32 v195, v195
	v_add_f32_e32 v164, 1.0, v164
	v_rcp_f32_e32 v216, v164
	v_add_f32_e32 v164, 1.0, v205
	v_rcp_f32_e32 v205, v164
	v_and_b32_e32 v164, 0xffff0000, v165
	v_add_f32_e32 v164, v111, v164
	v_add_f32_e32 v195, 1.0, v195
	v_mul_f32_e32 v164, 0xbfb8aa3b, v164
	v_rcp_f32_e32 v195, v195
	v_exp_f32_e32 v165, v164
	v_mul_f32_e32 v133, v133, v216
	s_mov_b64 s[42:43], -1
	v_mul_f32_e32 v164, v132, v195
	v_mul_f32_e32 v132, v134, v205
	v_add_f32_e32 v134, 1.0, v165
	v_lshlrev_b32_e32 v165, 16, v166
	v_and_b32_e32 v166, 0xffff0000, v166
	v_add_f32_e32 v165, v100, v165
	v_add_f32_e32 v166, v101, v166
	v_mul_f32_e32 v165, 0xbfb8aa3b, v165
	v_mul_f32_e32 v166, 0xbfb8aa3b, v166
	v_rcp_f32_e32 v134, v134
	v_exp_f32_e32 v165, v165
	v_exp_f32_e32 v166, v166
	s_and_b64 vcc, exec, s[4:5]
	v_mul_f32_e32 v134, v135, v134
	v_add_f32_e32 v135, 1.0, v165
	v_add_f32_e32 v165, 1.0, v166
	v_lshlrev_b32_e32 v166, 16, v167
	v_add_f32_e32 v166, v102, v166
	v_and_b32_e32 v167, 0xffff0000, v167
	v_mul_f32_e32 v166, 0xbfb8aa3b, v166
	v_add_f32_e32 v167, v103, v167
	v_exp_f32_e32 v166, v166
	v_mul_f32_e32 v167, 0xbfb8aa3b, v167
	v_exp_f32_e32 v167, v167
	v_rcp_f32_e32 v195, v165
	v_add_f32_e32 v165, 1.0, v166
	v_rcp_f32_e32 v166, v165
	v_add_f32_e32 v165, 1.0, v167
	v_rcp_f32_e32 v135, v135
	v_rcp_f32_e32 v205, v165
	v_mul_f32_e32 v167, v129, v195
	v_mul_f32_e32 v165, v128, v135
	v_mul_f32_e32 v135, v130, v166
	v_mul_f32_e32 v166, v131, v205
	s_cbranch_vccz .LBB0_873
	v_lshlrev_b32_e32 v128, 16, v160
	v_and_b32_e32 v129, 0xffff0000, v160
	v_add_f32_e32 v128, v164, v128
	v_add_f32_e32 v129, v133, v129
	v_cvt_pk_bf16_f32 v128, v128, v129
	v_lshlrev_b32_e32 v129, 16, v161
	v_and_b32_e32 v130, 0xffff0000, v161
	v_add_f32_e32 v129, v132, v129
	v_add_f32_e32 v130, v134, v130
	v_cvt_pk_bf16_f32 v129, v129, v130
	v_lshlrev_b32_e32 v130, 16, v162
	v_and_b32_e32 v131, 0xffff0000, v162
	v_add_f32_e32 v130, v165, v130
	v_add_f32_e32 v131, v167, v131
	v_cvt_pk_bf16_f32 v130, v130, v131
	v_lshlrev_b32_e32 v131, 16, v163
	v_add_f32_e32 v131, v135, v131
	v_and_b32_e32 v160, 0xffff0000, v163
	v_add_f32_e32 v160, v166, v160
	v_cvt_pk_bf16_f32 v131, v131, v160
	s_mov_b64 s[42:43], 0
